# P4 pass-0 reorder with the later code re-aligned to an 8-byte phase (one s_nop in an unreachable slot): the 4-mod-8 placement of the scan loops cost ~10 us
# speedup vs baseline: 1.0076x; 1.0026x over previous
.LBB0_900:
	v_readlane_b32 s0, v255, 60
	s_nop 0
	s_cmp_eq_u32 s0, 1
	s_cbranch_scc0 .Lp4_join
	s_mov_b32 s0, 2
	v_writelane_b32 v255, s0, 60
	v_lshlrev_b32_e32 v180, 4, v178
	s_branch .LBB0_796
	s_nop 0
